# hg_pass3: all stage-A loads hoisted to item start + SinT staged via LDS + batched stage C; phase 4 sample merged GEMMs spread over 24 WGs with per-tile flag chain, pass3 reversed WG order
# speedup vs baseline: 1.0802x; 1.0137x over previous
.LBB0_790:
	s_mov_b32 s2, s94
	s_cmp_gt_i32 s2, 23
	s_mov_b64 s[4:5], -1
	s_cbranch_scc0 .LBB0_816
	s_mov_b64 s[4:5], s[0:1]
	s_add_i32 s8, s94, -16
	s_cmpk_gt_i32 s8, 0x407
	s_cbranch_scc1 .LBB0_815
	s_load_dwordx4 s[16:19], s[4:5], 0xd8
	s_load_dwordx2 s[6:7], s[4:5], 0x78
	s_add_i32 s14, s8, -8
	s_add_i32 s22, s34, -24
	v_mbcnt_lo_u32_b32 v0, -1, 0
	s_waitcnt lgkmcnt(0)
	s_add_u32 s24, s18, 0x2030000
	s_addc_u32 s25, s19, 0
	s_add_u32 s30, s16, 0x3000000
	s_addc_u32 s33, s17, 0
	s_add_u32 s36, s18, 0x117b0000
	s_waitcnt vmcnt(3)
	v_mbcnt_hi_u32_b32 v28, -1, v0
	s_addc_u32 s37, s19, 0
	s_lshl_b32 s2, s8, 2
	s_lshl_b32 s3, s34, 2
	s_lshl_b32 s8, s8, 6
	s_lshl_b32 s11, s34, 6
	s_ashr_i32 s15, s14, 31
	s_ashr_i32 s23, s22, 31
	v_and_b32_e32 v0, 64, v28
	s_sub_i32 s2, s2, 32
	s_sub_i32 s3, s3, 32
	s_add_i32 s10, s8, 0xfffffe00
	s_addk_i32 s11, 0xfe00
	s_lshl_b64 s[8:9], s[14:15], 14
	s_lshl_b64 s[12:13], s[22:23], 14
	s_lshl_b64 s[26:27], s[14:15], 13
	s_lshl_b64 s[28:29], s[22:23], 13
	s_movk_i32 s15, 0x100
	v_mov_b32_e32 v17, 0
	s_mov_b32 s23, 0x127b0000
	s_mov_b32 s31, 0
	v_mov_b32_e32 v24, s37
	v_mov_b32_e32 v25, s33
	v_mov_b32_e32 v26, s36
	v_mov_b32_e32 v27, s30
	s_mov_b32 s33, 0x137b0000
	s_brev_b32 s42, 64
	s_movk_i32 s43, 0x1000
	s_movk_i32 s44, 0x2000
	s_mov_b32 s45, 0x2001000
	s_movk_i32 s46, 0x3000
	s_waitcnt vmcnt(2)
	v_xor_b32_e32 v29, 16, v28
	s_waitcnt vmcnt(1)
	v_add_u32_e32 v30, 64, v0
	v_xor_b32_e32 v31, 32, v28
	v_mov_b32_e32 v32, 0x358637bd
	s_mov_b32 s47, 0x800000
	s_movk_i32 s48, 0x3c00
	s_mov_b64 s[36:37], 0x1c00
	s_movk_i32 s49, 0x7fff
	s_movk_i32 s50, 0x110
	v_mov_b32_e32 v33, 0x3c00
	v_mov_b32_e32 v34, 1
	s_mov_b32 s51, s14
	s_branch .LBB0_794

.LBB0_796:
	s_sub_i32 s14, s34, s94
	s_add_i32 s14, s14, -1
	s_load_dwordx2 s[18:19], s[4:5], 0x40
	s_load_dwordx2 s[26:27], s[4:5], 0x70
	s_movk_i32 s2, 0x3c00
	s_mov_b32 s29, 0
	v_mov_b32_e32 v17, 0
	s_mov_b32 s3, 0x800000
	s_mov_b32 s10, 0x3f317217
	s_mov_b32 s11, 0x7f800000
	s_movk_i32 s23, 0x4000
	s_movk_i32 s33, 0x3000
	s_movk_i32 s42, 0x7000
	s_mov_b32 s43, 0xb000
	s_mov_b32 s44, 0xf000
	s_mov_b32 s45, 0x13000
	s_mov_b32 s46, 0x12000
	s_mov_b32 s47, 0x16000
	s_mov_b32 s48, 0x1a000
	s_mov_b32 s49, 0x1e000
	s_mov_b32 s50, 0x22000
	s_mov_b32 s51, 0x21000
	s_mov_b32 s52, 0x25000
	s_mov_b32 s53, 0x29000
	s_mov_b32 s54, 0x2d000
	s_mov_b32 s55, 0x31000
	s_mov_b32 s56, 0x30000
	s_mov_b32 s57, 0x34000
	s_mov_b32 s58, 0x38000
	s_mov_b32 s59, 0x8000
	s_mov_b32 s60, 0x17000
	s_mov_b32 s61, 0x26000
	s_mov_b32 s62, 0x35000
	s_add_i32 s63, 0, 0x19e00
	s_movk_i32 s64, 0x7fff
	s_movk_i32 s65, 0x880
	s_mov_b32 s66, 0x42a00000
	s_movk_i32 s67, 0x1100
	s_movk_i32 s68, 0x90
	s_add_i32 s69, 0, 0x13200
	s_movk_i32 s70, 0x110
	s_add_i32 s71, 0, 0x17a00
	s_mov_b32 s72, 0xffff0000
	s_add_i32 s73, 0, 0x1a600
	v_mov_b32_e32 v20, 0x358637bd
	v_mov_b32_e32 v21, 0x41b17218
	v_mov_b32_e32 v24, 1
	v_and_b32_e32 v176, 15, v156
	v_bfe_u32 v177, v156, 4, 2
	v_lshlrev_b32_e32 v177, 4, v177
	v_lshrrev_b32_e32 v178, 8, v156
	v_lshl_or_b32 v178, v178, 6, v176
	v_bfe_u32 v179, v156, 6, 2
	v_lshl_or_b32 v179, v179, 4, v176
	v_mad_u32_u24 v100, v178, s70, v177
	v_add_u32_e32 v100, 0x1a800, v100
	v_mad_u32_u24 v101, v178, s68, v177
	v_add_u32_e32 v101, 0x13200, v101
	v_mad_u32_u24 v102, v179, s68, v177
	v_add_u32_e32 v102, 0x17a00, v102
	v_mad_u32_u24 v103, v179, s70, v177
	v_add_u32_e32 v103, 0x4400, v103
	v_lshrrev_b32_e32 v96, 4, v156
	v_and_b32_e32 v97, 15, v156
	v_lshlrev_b32_e32 v97, 4, v97
	v_mad_u32_u24 v96, v96, s70, v97
	v_add_u32_e32 v96, 0x1a800, v96
	v_lshlrev_b32_e32 v97, 4, v156
	s_branch .LBB0_798

.LBB0_798:
	s_ashr_i32 s4, s14, 7
	v_mov_b32_e32 v25, v156
	s_ashr_i32 s5, s4, 31
	s_lshl_b64 s[30:31], s[4:5], 11
	v_ashrrev_i32_e32 v2, 7, v25
	s_lshl_b32 s4, s14, 6
	s_and_b32 s4, s4, 0x7c0
	v_lshlrev_b32_e32 v0, 4, v2
	s_or_b32 s30, s30, s4
	v_ashrrev_i32_e32 v1, 31, v0
	v_lshl_add_u64 v[4:5], s[30:31], 0, v[0:1]
	v_mov_b64_e32 v[6:7], s[24:25]
	v_mad_u64_u32 v[6:7], s[4:5], v4, s2, v[6:7]
	s_lshl_b32 s4, s14, 2
	v_and_b32_e32 v3, 0x7f, v25
	s_and_b32 s74, s4, 0x180
	v_mad_i32_i24 v7, v5, s2, v7
	s_lshl_b32 s28, s74, 1
	v_or_b32_e32 v1, s74, v3
	v_lshl_add_u64 v[4:5], v[6:7], 0, s[28:29]
	v_lshlrev_b32_e32 v16, 1, v3
	v_lshlrev_b32_e32 v1, 2, v1
	v_lshl_add_u64 v[4:5], v[4:5], 0, v[16:17]
	s_lshl_b32 s98, s14, 15
	s_add_u32 s98, s16, s98
	s_addc_u32 s99, s17, 0
	s_mov_b32 s100, 0x3c00
	s_mov_b32 s101, 0
	global_load_dwordx4 v[160:163], v97, s[98:99]
	s_add_u32 s98, s98, 0x2000
	s_addc_u32 s99, s99, 0
	global_load_dwordx4 v[164:167], v97, s[98:99]
	s_add_u32 s98, s98, 0x2000
	s_addc_u32 s99, s99, 0
	global_load_dwordx4 v[168:171], v97, s[98:99]
	s_add_u32 s98, s98, 0x2000
	s_addc_u32 s99, s99, 0
	global_load_dwordx4 v[172:175], v97, s[98:99]
	global_load_ushort v104, v[4:5], off
	global_load_ushort v105, v[4:5], off offset:1024
	global_load_ushort v106, v[4:5], off offset:2048
	v_lshl_add_u64 v[152:153], v[4:5], 0, s[100:101]
	global_load_ushort v107, v[152:153], off
	global_load_ushort v108, v[152:153], off offset:1024
	global_load_ushort v109, v[152:153], off offset:2048
	v_lshl_add_u64 v[154:155], v[152:153], 0, s[100:101]
	global_load_ushort v110, v[154:155], off
	global_load_ushort v111, v[154:155], off offset:1024
	global_load_ushort v112, v[154:155], off offset:2048
	v_lshl_add_u64 v[152:153], v[154:155], 0, s[100:101]
	global_load_ushort v113, v[152:153], off
	global_load_ushort v114, v[152:153], off offset:1024
	global_load_ushort v115, v[152:153], off offset:2048
	v_lshl_add_u64 v[154:155], v[152:153], 0, s[100:101]
	global_load_ushort v116, v[154:155], off
	global_load_ushort v117, v[154:155], off offset:1024
	global_load_ushort v118, v[154:155], off offset:2048
	v_lshl_add_u64 v[152:153], v[154:155], 0, s[100:101]
	global_load_ushort v119, v[152:153], off
	global_load_ushort v120, v[152:153], off offset:1024
	global_load_ushort v121, v[152:153], off offset:2048
	v_lshl_add_u64 v[154:155], v[152:153], 0, s[100:101]
	global_load_ushort v122, v[154:155], off
	global_load_ushort v123, v[154:155], off offset:1024
	global_load_ushort v124, v[154:155], off offset:2048
	v_lshl_add_u64 v[152:153], v[154:155], 0, s[100:101]
	global_load_ushort v125, v[152:153], off
	global_load_ushort v126, v[152:153], off offset:1024
	global_load_ushort v127, v[152:153], off offset:2048
	v_lshl_add_u64 v[154:155], v[152:153], 0, s[100:101]
	global_load_ushort v128, v[154:155], off
	global_load_ushort v129, v[154:155], off offset:1024
	global_load_ushort v130, v[154:155], off offset:2048
	v_lshl_add_u64 v[152:153], v[154:155], 0, s[100:101]
	global_load_ushort v131, v[152:153], off
	global_load_ushort v132, v[152:153], off offset:1024
	global_load_ushort v133, v[152:153], off offset:2048
	v_lshl_add_u64 v[154:155], v[152:153], 0, s[100:101]
	global_load_ushort v134, v[154:155], off
	global_load_ushort v135, v[154:155], off offset:1024
	global_load_ushort v136, v[154:155], off offset:2048
	v_lshl_add_u64 v[152:153], v[154:155], 0, s[100:101]
	global_load_ushort v137, v[152:153], off
	global_load_ushort v138, v[152:153], off offset:1024
	global_load_ushort v139, v[152:153], off offset:2048
	v_lshl_add_u64 v[154:155], v[152:153], 0, s[100:101]
	global_load_ushort v140, v[154:155], off
	global_load_ushort v141, v[154:155], off offset:1024
	global_load_ushort v142, v[154:155], off offset:2048
	v_lshl_add_u64 v[152:153], v[154:155], 0, s[100:101]
	global_load_ushort v143, v[152:153], off
	global_load_ushort v144, v[152:153], off offset:1024
	global_load_ushort v145, v[152:153], off offset:2048
	v_lshl_add_u64 v[154:155], v[152:153], 0, s[100:101]
	global_load_ushort v146, v[154:155], off
	global_load_ushort v147, v[154:155], off offset:1024
	global_load_ushort v148, v[154:155], off offset:2048
	v_lshl_add_u64 v[152:153], v[154:155], 0, s[100:101]
	global_load_ushort v149, v[152:153], off
	global_load_ushort v150, v[152:153], off offset:1024
	global_load_ushort v151, v[152:153], off offset:2048
	s_waitcnt lgkmcnt(0)
	global_load_dword v6, v1, s[18:19] offset:2048
	global_load_dword v7, v1, s[18:19]
	s_waitcnt vmcnt(0)
	v_mov_b32_e32 v10, v105
	s_nop 0
	v_mov_b32_e32 v1, v106
	v_mov_b32_e32 v11, v104
	v_add_co_u32_e32 v12, vcc, s23, v4
	s_waitcnt vmcnt(3)
	v_sub_f32_e32 v6, v6, v7
	v_addc_co_u32_e32 v13, vcc, 0, v5, vcc
	v_add_co_u32_e32 v14, vcc, s42, v4
	v_mul_f32_e32 v6, 0x3fb8aa3b, v6
	s_nop 0
	v_addc_co_u32_e32 v15, vcc, 0, v5, vcc
	v_mov_b32_e32 v28, v108
	v_mov_b32_e32 v29, v111
	v_add_co_u32_e32 v8, vcc, s33, v4
	v_exp_f32_e32 v6, v6
	s_nop 0
	v_addc_co_u32_e32 v9, vcc, 0, v5, vcc
	v_add_co_u32_e32 v18, vcc, s43, v4
	v_add_f32_e32 v6, 1.0, v6
	s_nop 0
	v_addc_co_u32_e32 v19, vcc, 0, v5, vcc
	v_add_co_u32_e32 v26, vcc, s44, v4
	s_waitcnt vmcnt(4)
	v_lshlrev_b32_e32 v7, 16, v10
	v_addc_co_u32_e32 v27, vcc, 0, v5, vcc
	v_mov_b32_e32 v30, v107
	v_mov_b32_e32 v31, v114
	v_mov_b32_e32 v32, v117
	s_nop 0
	v_mov_b32_e32 v8, v115
	s_nop 0
	v_mov_b32_e32 v18, v113
	s_nop 0
	v_mov_b32_e32 v19, v110
	v_mov_b32_e32 v9, v109
	v_div_scale_f32 v12, s[4:5], v6, v6, 1.0
	v_rcp_f32_e32 v14, v12
	v_mul_f32_e32 v7, 0xbfb8aa3b, v7
	v_exp_f32_e32 v7, v7
	v_div_scale_f32 v13, vcc, 1.0, v6, 1.0
	v_fma_f32 v15, -v12, v14, 1.0
	v_fmac_f32_e32 v14, v15, v14
	v_mul_f32_e32 v15, v13, v14
	v_add_f32_e32 v7, 1.0, v7
	v_rcp_f32_e32 v7, v7
	s_waitcnt vmcnt(9)
	v_lshlrev_b32_e32 v68, 16, v11
	s_waitcnt vmcnt(8)
	v_lshlrev_b32_e32 v10, 16, v28
	v_mul_f32_e32 v10, 0xbfb8aa3b, v10
	v_exp_f32_e32 v10, v10
	v_fma_f32 v28, -v12, v15, v13
	v_fmac_f32_e32 v15, v28, v14
	v_fma_f32 v12, -v12, v15, v13
	v_add_f32_e32 v10, 1.0, v10
	v_div_fmas_f32 v12, v12, v14, v15
	v_rcp_f32_e32 v10, v10
	v_div_fixup_f32 v51, v12, v6, 1.0
	v_sub_f32_e32 v48, 1.0, v51
	v_fma_f32 v6, v48, v7, v51
	v_cmp_gt_f32_e32 vcc, s3, v6
	v_fma_f32 v12, v48, v10, v51
	v_cmp_gt_f32_e64 s[4:5], s3, v12
	v_cndmask_b32_e64 v7, 0, 32, vcc
	v_ldexp_f32 v7, v6, v7
	v_cndmask_b32_e64 v10, 0, 32, s[4:5]
	v_log_f32_e32 v7, v7
	v_ldexp_f32 v10, v12, v10
	v_log_f32_e32 v13, v10
	s_waitcnt vmcnt(7)
	v_lshlrev_b32_e32 v11, 16, v29
	v_mul_f32_e32 v14, 0x3f317217, v7
	v_fma_f32 v14, v7, s10, -v14
	v_mul_f32_e32 v15, 0x3f317217, v13
	v_fmac_f32_e32 v14, 0x3377d1cf, v7
	v_sub_f32_e32 v10, 1.0, v6
	v_cndmask_b32_e32 v6, 0, v21, vcc
	v_fma_f32 v15, v13, s10, -v15
	v_fmac_f32_e32 v14, 0x3f317217, v7
	v_cmp_lt_f32_e64 vcc, |v7|, s11
	v_mul_f32_e32 v11, 0xbfb8aa3b, v11
	v_fmac_f32_e32 v15, 0x3377d1cf, v13
	v_cndmask_b32_e32 v7, v7, v14, vcc
	v_exp_f32_e32 v11, v11
	v_fmac_f32_e32 v15, 0x3f317217, v13
	v_cmp_lt_f32_e64 vcc, |v13|, s11
	v_sub_f32_e32 v6, v7, v6
	v_add_f32_e32 v37, 0, v6
	v_cndmask_b32_e32 v13, v13, v15, vcc
	v_add_co_u32_e32 v6, vcc, s45, v4
	v_add_f32_e32 v11, 1.0, v11
	s_nop 0
	v_addc_co_u32_e32 v7, vcc, 0, v5, vcc
	v_mov_b32_e32 v28, v120
	v_rcp_f32_e32 v11, v11
	v_cndmask_b32_e64 v14, 0, v21, s[4:5]
	v_sub_f32_e32 v13, v13, v14
	v_add_f32_e32 v39, v37, v13
	v_fma_f32 v29, v48, v11, v51
	v_cmp_gt_f32_e32 vcc, s3, v29
	s_waitcnt vmcnt(7)
	v_lshlrev_b32_e32 v69, 16, v30
	s_waitcnt vmcnt(2)
	v_lshlrev_b32_e32 v70, 16, v19
	v_cndmask_b32_e64 v11, 0, 32, vcc
	v_ldexp_f32 v11, v29, v11
	v_log_f32_e32 v33, v11
	v_sub_f32_e32 v11, 1.0, v12
	v_lshlrev_b32_e32 v12, 16, v31
	v_mul_f32_e32 v31, 0xbfb8aa3b, v12
	v_add_co_u32_e64 v12, s[4:5], s46, v4
	v_mul_f32_e32 v30, 0x3f317217, v33
	s_nop 0
	v_addc_co_u32_e64 v13, s[4:5], 0, v5, s[4:5]
	v_add_co_u32_e64 v14, s[4:5], s47, v4
	v_lshlrev_b32_e32 v71, 16, v18
	s_nop 0
	v_addc_co_u32_e64 v15, s[4:5], 0, v5, s[4:5]
	v_mov_b32_e32 v34, v119
	v_mov_b32_e32 v35, v123
	v_mov_b32_e32 v36, v122
	s_nop 0
	v_mov_b32_e32 v13, v121
	v_mov_b32_e32 v12, v118
	v_mov_b32_e32 v38, v116
	v_exp_f32_e32 v6, v31
	v_cndmask_b32_e32 v14, 0, v21, vcc
	v_fma_f32 v7, v33, s10, -v30
	v_fmac_f32_e32 v7, 0x3377d1cf, v33
	v_add_f32_e32 v6, 1.0, v6
	v_rcp_f32_e32 v6, v6
	v_fmac_f32_e32 v7, 0x3f317217, v33
	v_cmp_lt_f32_e64 s[4:5], |v33|, s11
	v_lshlrev_b32_e32 v27, 16, v32
	v_fma_f32 v15, v48, v6, v51
	v_cmp_gt_f32_e32 vcc, s3, v15
	v_cndmask_b32_e64 v7, v33, v7, s[4:5]
	v_sub_f32_e32 v7, v7, v14
	v_cndmask_b32_e64 v6, 0, 32, vcc
	v_ldexp_f32 v6, v15, v6
	v_log_f32_e32 v26, v6
	v_add_f32_e32 v41, v39, v7
	v_sub_f32_e32 v14, 1.0, v29
	v_mul_f32_e32 v27, 0xbfb8aa3b, v27
	v_mul_f32_e32 v6, 0x3f317217, v26
	v_fma_f32 v19, v26, s10, -v6
	v_add_co_u32_e64 v6, s[4:5], s48, v4
	v_exp_f32_e32 v27, v27
	s_nop 0
	v_addc_co_u32_e64 v7, s[4:5], 0, v5, s[4:5]
	v_mov_b32_e32 v29, v126
	v_fmac_f32_e32 v19, 0x3377d1cf, v26
	v_fmac_f32_e32 v19, 0x3f317217, v26
	v_cmp_lt_f32_e64 s[4:5], |v26|, s11
	v_sub_f32_e32 v15, 1.0, v15
	s_waitcnt vmcnt(7)
	v_lshlrev_b32_e32 v28, 16, v28
	v_cndmask_b32_e64 v19, v26, v19, s[4:5]
	v_cndmask_b32_e32 v26, 0, v21, vcc
	v_sub_f32_e32 v19, v19, v26
	v_add_f32_e32 v26, 1.0, v27
	v_rcp_f32_e32 v26, v26
	v_mul_f32_e32 v28, 0xbfb8aa3b, v28
	v_add_f32_e32 v43, v41, v19
	v_exp_f32_e32 v28, v28
	v_fma_f32 v30, v48, v26, v51
	v_add_co_u32_e64 v26, s[4:5], s49, v4
	v_cmp_gt_f32_e32 vcc, s3, v30
	s_nop 0
	v_addc_co_u32_e64 v27, s[4:5], 0, v5, s[4:5]
	v_mov_b32_e32 v31, v129
	v_cndmask_b32_e64 v18, 0, 32, vcc
	v_ldexp_f32 v18, v30, v18
	v_log_f32_e32 v18, v18
	s_waitcnt vmcnt(7)
	v_lshlrev_b32_e32 v73, 16, v34
	v_mul_f32_e32 v19, 0x3f317217, v18
	v_fma_f32 v19, v18, s10, -v19
	v_fmac_f32_e32 v19, 0x3377d1cf, v18
	v_fmac_f32_e32 v19, 0x3f317217, v18
	v_cmp_lt_f32_e64 s[4:5], |v18|, s11
	s_waitcnt vmcnt(2)
	v_lshlrev_b32_e32 v72, 16, v38
	v_lshlrev_b32_e32 v74, 16, v36
	v_cndmask_b32_e64 v18, v18, v19, s[4:5]
	v_add_f32_e32 v19, 1.0, v28
	v_rcp_f32_e32 v19, v19
	v_cndmask_b32_e32 v28, 0, v21, vcc
	v_sub_f32_e32 v18, v18, v28
	v_add_f32_e32 v49, v43, v18
	v_fma_f32 v28, v48, v19, v51
	v_cmp_gt_f32_e32 vcc, s3, v28
	s_waitcnt vmcnt(1)
	v_lshlrev_b32_e32 v29, 16, v29
	v_cndmask_b32_e64 v18, 0, 32, vcc
	v_ldexp_f32 v18, v28, v18
	v_log_f32_e32 v32, v18
	v_add_co_u32_e64 v18, s[4:5], s50, v4
	v_mul_f32_e32 v29, 0xbfb8aa3b, v29
	s_nop 0
	v_addc_co_u32_e64 v19, s[4:5], 0, v5, s[4:5]
	v_mov_b32_e32 v40, v132
	s_nop 0
	v_mov_b32_e32 v19, v133
	s_nop 0
	v_mov_b32_e32 v18, v130
	v_mov_b32_e32 v42, v128
	s_nop 0
	v_mov_b32_e32 v26, v127
	v_mov_b32_e32 v44, v125
	v_lshlrev_b32_e32 v7, 16, v35
	v_mul_f32_e32 v7, 0xbfb8aa3b, v7
	v_exp_f32_e32 v7, v7
	v_mul_f32_e32 v6, 0x3f317217, v32
	v_fma_f32 v6, v32, s10, -v6
	v_fmac_f32_e32 v6, 0x3377d1cf, v32
	v_add_f32_e32 v7, 1.0, v7
	v_rcp_f32_e32 v7, v7
	v_fmac_f32_e32 v6, 0x3f317217, v32
	v_cmp_lt_f32_e64 s[4:5], |v32|, s11
	v_sub_f32_e32 v27, 1.0, v30
	v_cndmask_b32_e32 v30, 0, v21, vcc
	v_cndmask_b32_e64 v6, v32, v6, s[4:5]
	v_sub_f32_e32 v6, v6, v30
	v_fma_f32 v30, v48, v7, v51
	v_cmp_gt_f32_e32 vcc, s3, v30
	v_add_f32_e32 v53, v49, v6
	v_exp_f32_e32 v29, v29
	v_cndmask_b32_e64 v7, 0, 32, vcc
	v_ldexp_f32 v7, v30, v7
	v_log_f32_e32 v7, v7
	v_cndmask_b32_e32 v33, 0, v21, vcc
	v_sub_f32_e32 v28, 1.0, v28
	v_mul_f32_e32 v6, 0x3f317217, v7
	v_fma_f32 v6, v7, s10, -v6
	v_fmac_f32_e32 v6, 0x3377d1cf, v7
	v_fmac_f32_e32 v6, 0x3f317217, v7
	v_cmp_lt_f32_e64 s[4:5], |v7|, s11
	s_waitcnt vmcnt(2)
	v_lshlrev_b32_e32 v76, 16, v42
	v_cndmask_b32_e64 v32, v7, v6, s[4:5]
	v_add_f32_e32 v6, 1.0, v29
	v_rcp_f32_e32 v29, v6
	v_add_co_u32_e32 v6, vcc, s52, v4
	v_sub_f32_e32 v32, v32, v33
	s_nop 0
	v_addc_co_u32_e32 v7, vcc, 0, v5, vcc
	v_mov_b32_e32 v34, v135
	v_fma_f32 v35, v48, v29, v51
	v_cmp_gt_f32_e32 vcc, s3, v35
	v_add_f32_e32 v54, v53, v32
	s_waitcnt vmcnt(1)
	v_lshlrev_b32_e32 v75, 16, v44
	v_cndmask_b32_e64 v29, 0, 32, vcc
	v_ldexp_f32 v29, v35, v29
	v_log_f32_e32 v38, v29
	v_sub_f32_e32 v29, 1.0, v30
	v_lshlrev_b32_e32 v30, 16, v31
	v_mul_f32_e32 v30, 0xbfb8aa3b, v30
	v_exp_f32_e32 v45, v30
	v_add_co_u32_e64 v30, s[4:5], s51, v4
	v_mul_f32_e32 v36, 0x3f317217, v38
	s_nop 0
	v_addc_co_u32_e64 v31, s[4:5], 0, v5, s[4:5]
	v_add_co_u32_e64 v32, s[4:5], s53, v4
	v_mov_b32_e32 v50, v131
	s_nop 0
	v_addc_co_u32_e64 v33, s[4:5], 0, v5, s[4:5]
	v_mov_b32_e32 v52, v138
	v_fma_f32 v30, v38, s10, -v36
	v_fmac_f32_e32 v30, 0x3377d1cf, v38
	v_fmac_f32_e32 v30, 0x3f317217, v38
	v_cmp_lt_f32_e64 s[4:5], |v38|, s11
	v_cndmask_b32_e32 v36, 0, v21, vcc
	v_add_f32_e32 v31, 1.0, v45
	v_cndmask_b32_e64 v30, v38, v30, s[4:5]
	v_sub_f32_e32 v30, v30, v36
	v_add_f32_e32 v55, v54, v30
	v_lshlrev_b32_e32 v30, 16, v40
	v_add_co_u32_e64 v44, s[4:5], s54, v4
	v_mul_f32_e32 v40, 0xbfb8aa3b, v30
	s_nop 0
	v_addc_co_u32_e64 v45, s[4:5], 0, v5, s[4:5]
	v_rcp_f32_e32 v31, v31
	v_mov_b32_e32 v59, v141
	v_mov_b32_e32 v61, v140
	v_mov_b32_e32 v30, v139
	v_mov_b32_e32 v60, v137
	v_mov_b32_e32 v62, v134
	v_exp_f32_e32 v6, v40
	v_fma_f32 v36, v48, v31, v51
	v_cmp_gt_f32_e32 vcc, s3, v36
	v_add_f32_e32 v6, 1.0, v6
	v_rcp_f32_e32 v6, v6
	v_cndmask_b32_e64 v31, 0, 32, vcc
	v_ldexp_f32 v31, v36, v31
	v_log_f32_e32 v38, v31
	v_fma_f32 v33, v48, v6, v51
	v_cndmask_b32_e32 v32, 0, v21, vcc
	v_cmp_gt_f32_e32 vcc, s3, v33
	v_sub_f32_e32 v31, 1.0, v35
	v_mul_f32_e32 v35, 0x3f317217, v38
	v_cndmask_b32_e64 v6, 0, 32, vcc
	v_ldexp_f32 v6, v33, v6
	v_fma_f32 v7, v38, s10, -v35
	v_log_f32_e32 v35, v6
	v_fmac_f32_e32 v7, 0x3377d1cf, v38
	v_fmac_f32_e32 v7, 0x3f317217, v38
	v_cmp_lt_f32_e64 s[4:5], |v38|, s11
	v_mul_f32_e32 v6, 0x3f317217, v35
	v_sub_f32_e32 v33, 1.0, v33
	v_cndmask_b32_e64 v7, v38, v7, s[4:5]
	v_sub_f32_e32 v7, v7, v32
	v_sub_f32_e32 v32, 1.0, v36
	v_fma_f32 v36, v35, s10, -v6
	v_add_co_u32_e64 v6, s[4:5], s55, v4
	v_add_f32_e32 v56, v55, v7
	s_nop 0
	v_addc_co_u32_e64 v7, s[4:5], 0, v5, s[4:5]
	v_mov_b32_e32 v40, v144
	v_fmac_f32_e32 v36, 0x3377d1cf, v35
	v_fmac_f32_e32 v36, 0x3f317217, v35
	v_cmp_lt_f32_e64 s[4:5], |v35|, s11
	s_waitcnt vmcnt(8)
	v_lshlrev_b32_e32 v34, 16, v34
	v_mul_f32_e32 v34, 0xbfb8aa3b, v34
	v_exp_f32_e32 v34, v34
	v_cndmask_b32_e64 v35, v35, v36, s[4:5]
	v_cndmask_b32_e32 v36, 0, v21, vcc
	v_sub_f32_e32 v35, v35, v36
	v_add_f32_e32 v34, 1.0, v34
	v_rcp_f32_e32 v34, v34
	v_add_co_u32_e64 v46, s[4:5], s57, v4
	v_add_f32_e32 v57, v56, v35
	v_fma_f32 v36, v48, v34, v51
	v_cmp_gt_f32_e32 vcc, s3, v36
	v_addc_co_u32_e64 v47, s[4:5], 0, v5, s[4:5]
	s_nop 0
	v_cndmask_b32_e64 v34, 0, 32, vcc
	v_mov_b32_e32 v42, v147
	v_ldexp_f32 v34, v36, v34
	v_log_f32_e32 v38, v34
	s_waitcnt vmcnt(8)
	v_lshlrev_b32_e32 v77, 16, v50
	s_waitcnt vmcnt(7)
	v_lshlrev_b32_e32 v35, 16, v52
	v_mul_f32_e32 v35, 0xbfb8aa3b, v35
	v_exp_f32_e32 v35, v35
	v_mul_f32_e32 v34, 0x3f317217, v38
	v_fma_f32 v50, v38, s10, -v34
	v_fmac_f32_e32 v50, 0x3377d1cf, v38
	v_add_f32_e32 v34, 1.0, v35
	v_rcp_f32_e32 v52, v34
	v_add_co_u32_e64 v34, s[4:5], s56, v4
	v_fmac_f32_e32 v50, 0x3f317217, v38
	s_nop 0
	v_addc_co_u32_e64 v35, s[4:5], 0, v5, s[4:5]
	v_add_co_u32_e64 v64, s[4:5], s58, v4
	s_waitcnt vmcnt(5)
	v_lshlrev_b32_e32 v80, 16, v61
	v_addc_co_u32_e64 v65, s[4:5], 0, v5, s[4:5]
	v_mov_b32_e32 v63, v143
	v_mov_b32_e32 v66, v150
	v_cmp_lt_f32_e64 s[4:5], |v38|, s11
	v_cndmask_b32_e32 v35, 0, v21, vcc
	s_waitcnt vmcnt(5)
	v_lshlrev_b32_e32 v79, 16, v60
	v_cndmask_b32_e64 v34, v38, v50, s[4:5]
	v_sub_f32_e32 v34, v34, v35
	v_fma_f32 v35, v48, v52, v51
	v_mov_b32_e32 v52, v149
	s_nop 0
	v_mov_b32_e32 v46, v146
	v_lshlrev_b32_e32 v50, 16, v59
	v_cmp_gt_f32_e32 vcc, s3, v35
	v_mul_f32_e32 v50, 0xbfb8aa3b, v50
	v_exp_f32_e32 v50, v50
	v_cndmask_b32_e64 v38, 0, 32, vcc
	v_ldexp_f32 v38, v35, v38
	v_log_f32_e32 v38, v38
	v_add_f32_e32 v47, 1.0, v50
	v_rcp_f32_e32 v47, v47
	v_add_f32_e32 v58, v57, v34
	v_sub_f32_e32 v34, 1.0, v36
	v_mul_f32_e32 v36, 0x3f317217, v38
	v_fma_f32 v36, v38, s10, -v36
	v_fmac_f32_e32 v36, 0x3377d1cf, v38
	v_fmac_f32_e32 v36, 0x3f317217, v38
	v_cmp_lt_f32_e64 s[4:5], |v38|, s11
	v_fma_f32 v47, v48, v47, v51
	s_waitcnt vmcnt(6)
	v_lshlrev_b32_e32 v78, 16, v62
	v_cndmask_b32_e64 v36, v38, v36, s[4:5]
	v_cndmask_b32_e32 v38, 0, v21, vcc
	v_cmp_gt_f32_e32 vcc, s3, v47
	v_sub_f32_e32 v36, v36, v38
	v_add_f32_e32 v59, v58, v36
	v_cndmask_b32_e64 v38, 0, 32, vcc
	v_ldexp_f32 v38, v47, v38
	v_log_f32_e32 v50, v38
	v_sub_f32_e32 v38, 1.0, v35
	v_mov_b32_e32 v36, v145
	v_mov_b32_e32 v35, v142
	s_waitcnt vmcnt(7)
	v_lshlrev_b32_e32 v6, 16, v40
	v_mul_f32_e32 v6, 0xbfb8aa3b, v6
	v_exp_f32_e32 v6, v6
	v_mul_f32_e32 v60, 0x3f317217, v50
	v_fma_f32 v7, v50, s10, -v60
	v_fmac_f32_e32 v7, 0x3377d1cf, v50
	v_add_f32_e32 v6, 1.0, v6
	v_rcp_f32_e32 v6, v6
	v_fmac_f32_e32 v7, 0x3f317217, v50
	v_cmp_lt_f32_e64 s[4:5], |v50|, s11
	v_cndmask_b32_e32 v40, 0, v21, vcc
	v_fma_f32 v6, v48, v6, v51
	v_cndmask_b32_e64 v7, v50, v7, s[4:5]
	v_cmp_gt_f32_e32 vcc, s3, v6
	v_sub_f32_e32 v7, v7, v40
	v_add_f32_e32 v60, v59, v7
	v_cndmask_b32_e64 v40, 0, 32, vcc
	v_ldexp_f32 v40, v6, v40
	v_log_f32_e32 v44, v40
	v_sub_f32_e32 v40, 1.0, v47
	s_waitcnt vmcnt(6)
	v_lshlrev_b32_e32 v42, 16, v42
	v_mul_f32_e32 v42, 0xbfb8aa3b, v42
	v_exp_f32_e32 v42, v42
	v_mul_f32_e32 v7, 0x3f317217, v44
	v_fma_f32 v7, v44, s10, -v7
	v_fmac_f32_e32 v7, 0x3377d1cf, v44
	v_add_f32_e32 v42, 1.0, v42
	v_rcp_f32_e32 v42, v42
	v_fmac_f32_e32 v7, 0x3f317217, v44
	v_cmp_lt_f32_e64 s[4:5], |v44|, s11
	s_waitcnt vmcnt(5)
	v_lshlrev_b32_e32 v81, 16, v63
	v_cndmask_b32_e64 v7, v44, v7, s[4:5]
	v_cndmask_b32_e32 v44, 0, v21, vcc
	v_sub_f32_e32 v7, v7, v44
	v_fma_f32 v44, v48, v42, v51
	v_add_f32_e32 v61, v60, v7
	s_waitcnt vmcnt(4)
	v_lshlrev_b32_e32 v7, 16, v66
	v_cmp_gt_f32_e32 vcc, s3, v44
	v_mul_f32_e32 v7, 0xbfb8aa3b, v7
	v_exp_f32_e32 v7, v7
	v_cndmask_b32_e64 v42, 0, 32, vcc
	v_ldexp_f32 v42, v44, v42
	v_log_f32_e32 v45, v42
	v_add_f32_e32 v7, 1.0, v7
	v_rcp_f32_e32 v7, v7
	v_sub_f32_e32 v42, 1.0, v6
	v_mul_f32_e32 v6, 0x3f317217, v45
	v_fma_f32 v6, v45, s10, -v6
	v_fmac_f32_e32 v6, 0x3377d1cf, v45
	v_fmac_f32_e32 v6, 0x3f317217, v45
	v_cmp_lt_f32_e64 s[4:5], |v45|, s11
	v_fmac_f32_e32 v51, v48, v7
	s_waitcnt vmcnt(2)
	v_lshlrev_b32_e32 v82, 16, v46
	v_cndmask_b32_e64 v6, v45, v6, s[4:5]
	v_cndmask_b32_e32 v45, 0, v21, vcc
	v_cmp_gt_f32_e32 vcc, s3, v51
	v_sub_f32_e32 v6, v6, v45
	v_add_f32_e32 v62, v61, v6
	v_cndmask_b32_e64 v7, 0, 32, vcc
	v_ldexp_f32 v7, v51, v7
	v_log_f32_e32 v7, v7
	v_sub_f32_e32 v44, 1.0, v44
	v_sub_f32_e32 v51, 1.0, v51
	v_mul_f32_e32 v6, 0x3f317217, v7
	v_fma_f32 v6, v7, s10, -v6
	v_fmac_f32_e32 v6, 0x3377d1cf, v7
	v_fmac_f32_e32 v6, 0x3f317217, v7
	v_cmp_lt_f32_e64 s[4:5], |v7|, s11
	s_nop 1
	v_cndmask_b32_e64 v6, v7, v6, s[4:5]
	v_cndmask_b32_e32 v7, 0, v21, vcc
	v_sub_f32_e32 v6, v6, v7
	v_add_f32_e32 v63, v62, v6
	v_add_co_u32_e32 v6, vcc, s59, v4
	s_nop 1
	v_addc_co_u32_e32 v7, vcc, 0, v5, vcc
	v_add_co_u32_e32 v46, vcc, s60, v4
	s_nop 1
	v_addc_co_u32_e32 v47, vcc, 0, v5, vcc
	v_add_co_u32_e32 v66, vcc, s61, v4
	s_nop 1
	v_addc_co_u32_e32 v67, vcc, 0, v5, vcc
	v_add_co_u32_e32 v4, vcc, s62, v4
	s_nop 1
	v_addc_co_u32_e32 v5, vcc, 0, v5, vcc
	v_mov_b32_e32 v50, v112
	v_mov_b32_e32 v48, v124
	s_nop 0
	v_mov_b32_e32 v46, v136
	v_mov_b32_e32 v45, v148
	v_mov_b32_e32 v47, v151
	v_lshl_add_u32 v4, v25, 2, s63
	v_lshl_add_u32 v6, v3, 2, s63
	ds_write_b32 v4, v63
	s_waitcnt lgkmcnt(0)
	s_barrier
	ds_read2st64_b32 v[4:5], v6 offset1:2
	v_lshlrev_b32_e32 v64, 16, v52
	ds_read_b32 v52, v6 offset:1024
	v_cmp_lt_i32_e32 vcc, 0, v2
	v_mul_lo_u32 v66, v2, s65
	v_or_b32_e32 v66, v66, v3
	s_waitcnt lgkmcnt(1)
	v_cndmask_b32_e32 v4, 0, v4, vcc
	v_cmp_lt_i32_e32 vcc, 1, v2
	v_lshl_add_u32 v66, v66, 1, 0
	s_nop 0
	v_cndmask_b32_e32 v6, 0, v5, vcc
	v_cmp_lt_i32_e32 vcc, 2, v2
	v_add_f32_e32 v4, v4, v6
	s_waitcnt lgkmcnt(0)
	v_cndmask_b32_e32 v6, 0, v52, vcc
	v_add_f32_e32 v4, v4, v6
	v_mul_f32_e32 v4, 0x3fb8aa3b, v4
	v_mad_u64_u32 v[6:7], s[4:5], v2, v2, v[2:3]
	v_exp_f32_e32 v65, v4
	v_lshrrev_b32_e32 v4, 31, v6
	v_add_u32_e32 v4, v6, v4
	v_mul_f32_e32 v6, 0x3fb8aa3b, v37
	v_exp_f32_e32 v6, v6
	v_lshrrev_b32_e32 v4, 1, v4
	v_add_u32_e32 v7, v4, v2
	v_add_u32_e32 v4, 0, v16
	v_mul_f32_e32 v6, v6, v68
	v_bfe_u32 v16, v6, 16, 1
	v_add3_u32 v16, v6, v16, s64
	ds_write_b16_d16_hi v66, v16
	v_min_f32_e64 v16, -v37, s66
	v_mul_f32_e32 v16, 0x3fb8aa3b, v16
	v_exp_f32_e32 v16, v16
	v_mul_f32_e32 v6, v6, v65
	v_bfe_u32 v67, v6, 16, 1
	v_add3_u32 v6, v6, v67, s64
	ds_write_b16_d16_hi v66, v6 offset:17408
	v_mul_f32_e32 v6, v10, v16
	v_bfe_u32 v16, v6, 16, 1
	v_add3_u32 v16, v6, v16, s64
	v_mul_f32_e32 v6, 0x3fb8aa3b, v39
	v_exp_f32_e32 v67, v6
	v_mad_u64_u32 v[6:7], s[4:5], v7, s67, v[4:5]
	ds_write_b16_d16_hi v6, v16 offset:34816
	v_mul_f32_e32 v7, v67, v69
	v_bfe_u32 v16, v7, 16, 1
	v_add3_u32 v16, v7, v16, s64
	ds_write_b16_d16_hi v66, v16 offset:272
	v_min_f32_e64 v16, -v39, s66
	v_mul_f32_e32 v16, 0x3fb8aa3b, v16
	v_exp_f32_e32 v16, v16
	v_mul_f32_e32 v7, v7, v65
	v_bfe_u32 v67, v7, 16, 1
	v_add3_u32 v7, v7, v67, s64
	ds_write_b16_d16_hi v66, v7 offset:17680
	v_mul_f32_e32 v7, v11, v16
	v_mul_f32_e32 v16, 0x3fb8aa3b, v41
	v_exp_f32_e32 v16, v16
	v_bfe_u32 v67, v7, 16, 1
	v_add3_u32 v7, v7, v67, s64
	ds_write_b16_d16_hi v6, v7 offset:35088
	v_mul_f32_e32 v7, v16, v70
	v_bfe_u32 v16, v7, 16, 1
	v_add3_u32 v16, v7, v16, s64
	ds_write_b16_d16_hi v66, v16 offset:544
	v_min_f32_e64 v16, -v41, s66
	v_mul_f32_e32 v16, 0x3fb8aa3b, v16
	v_exp_f32_e32 v16, v16
	v_mul_f32_e32 v7, v7, v65
	v_bfe_u32 v67, v7, 16, 1
	v_add3_u32 v7, v7, v67, s64
	ds_write_b16_d16_hi v66, v7 offset:17952
	v_mul_f32_e32 v7, v14, v16
	v_mul_f32_e32 v16, 0x3fb8aa3b, v43
	v_exp_f32_e32 v16, v16
	v_bfe_u32 v67, v7, 16, 1
	v_add3_u32 v7, v7, v67, s64
	ds_write_b16_d16_hi v6, v7 offset:35360
	v_mul_f32_e32 v7, v16, v71
	v_bfe_u32 v16, v7, 16, 1
	v_add3_u32 v16, v7, v16, s64
	ds_write_b16_d16_hi v66, v16 offset:816
	v_min_f32_e64 v16, -v43, s66
	v_mul_f32_e32 v16, 0x3fb8aa3b, v16
	v_exp_f32_e32 v16, v16
	v_mul_f32_e32 v7, v7, v65
	v_bfe_u32 v67, v7, 16, 1
	v_add3_u32 v7, v7, v67, s64
	ds_write_b16_d16_hi v66, v7 offset:18224
	v_mul_f32_e32 v7, v15, v16
	v_mul_f32_e32 v16, 0x3fb8aa3b, v49
	v_exp_f32_e32 v16, v16
	v_bfe_u32 v67, v7, 16, 1
	v_add3_u32 v7, v7, v67, s64
	ds_write_b16_d16_hi v6, v7 offset:35632
	v_mul_f32_e32 v7, v16, v72
	v_bfe_u32 v16, v7, 16, 1
	v_add3_u32 v16, v7, v16, s64
	ds_write_b16_d16_hi v66, v16 offset:1088
	v_min_f32_e64 v16, -v49, s66
	v_mul_f32_e32 v16, 0x3fb8aa3b, v16
	v_exp_f32_e32 v16, v16
	v_mul_f32_e32 v7, v7, v65
	v_bfe_u32 v67, v7, 16, 1
	v_add3_u32 v7, v7, v67, s64
	ds_write_b16_d16_hi v66, v7 offset:18496
	v_mul_f32_e32 v7, v27, v16
	v_mul_f32_e32 v16, 0x3fb8aa3b, v53
	v_exp_f32_e32 v16, v16
	v_bfe_u32 v67, v7, 16, 1
	v_add3_u32 v7, v7, v67, s64
	ds_write_b16_d16_hi v6, v7 offset:35904
	v_mul_f32_e32 v7, v16, v73
	v_bfe_u32 v16, v7, 16, 1
	v_add3_u32 v16, v7, v16, s64
	ds_write_b16_d16_hi v66, v16 offset:1360
	v_min_f32_e64 v16, -v53, s66
	v_mul_f32_e32 v16, 0x3fb8aa3b, v16
	v_exp_f32_e32 v16, v16
	v_mul_f32_e32 v7, v7, v65
	v_bfe_u32 v67, v7, 16, 1
	v_add3_u32 v7, v7, v67, s64
	ds_write_b16_d16_hi v66, v7 offset:18768
	v_mul_f32_e32 v7, v28, v16
	v_mul_f32_e32 v16, 0x3fb8aa3b, v54
	v_exp_f32_e32 v16, v16
	v_bfe_u32 v67, v7, 16, 1
	v_add3_u32 v7, v7, v67, s64
	ds_write_b16_d16_hi v6, v7 offset:36176
	v_mul_f32_e32 v7, v16, v74
	v_bfe_u32 v16, v7, 16, 1
	v_add3_u32 v16, v7, v16, s64
	ds_write_b16_d16_hi v66, v16 offset:1632
	v_min_f32_e64 v16, -v54, s66
	v_mul_f32_e32 v16, 0x3fb8aa3b, v16
	v_exp_f32_e32 v16, v16
	v_mul_f32_e32 v7, v7, v65
	v_bfe_u32 v67, v7, 16, 1
	v_add3_u32 v7, v7, v67, s64
	ds_write_b16_d16_hi v66, v7 offset:19040
	v_mul_f32_e32 v7, v29, v16
	v_mul_f32_e32 v16, 0x3fb8aa3b, v55
	v_exp_f32_e32 v16, v16
	v_bfe_u32 v67, v7, 16, 1
	v_add3_u32 v7, v7, v67, s64
	ds_write_b16_d16_hi v6, v7 offset:36448
	v_mul_f32_e32 v7, v16, v75
	v_bfe_u32 v16, v7, 16, 1
	v_add3_u32 v16, v7, v16, s64
	ds_write_b16_d16_hi v66, v16 offset:1904
	v_min_f32_e64 v16, -v55, s66
	v_mul_f32_e32 v16, 0x3fb8aa3b, v16
	v_exp_f32_e32 v16, v16
	v_mul_f32_e32 v7, v7, v65
	v_bfe_u32 v67, v7, 16, 1
	v_add3_u32 v7, v7, v67, s64
	ds_write_b16_d16_hi v66, v7 offset:19312
	v_mul_f32_e32 v7, v31, v16
	v_mul_f32_e32 v16, 0x3fb8aa3b, v56
	v_exp_f32_e32 v16, v16
	v_bfe_u32 v67, v7, 16, 1
	v_add3_u32 v7, v7, v67, s64
	ds_write_b16_d16_hi v6, v7 offset:36720
	v_mul_f32_e32 v7, v16, v76
	v_bfe_u32 v16, v7, 16, 1
	v_add3_u32 v16, v7, v16, s64
	ds_write_b16_d16_hi v66, v16 offset:2176
	v_min_f32_e64 v16, -v56, s66
	v_mul_f32_e32 v16, 0x3fb8aa3b, v16
	v_exp_f32_e32 v16, v16
	v_mul_f32_e32 v7, v7, v65
	v_bfe_u32 v67, v7, 16, 1
	v_add3_u32 v7, v7, v67, s64
	ds_write_b16_d16_hi v66, v7 offset:19584
	v_mul_f32_e32 v7, v32, v16
	v_mul_f32_e32 v16, 0x3fb8aa3b, v57
	v_exp_f32_e32 v16, v16
	v_bfe_u32 v67, v7, 16, 1
	v_add3_u32 v7, v7, v67, s64
	ds_write_b16_d16_hi v6, v7 offset:36992
	v_mul_f32_e32 v7, v16, v77
	v_bfe_u32 v16, v7, 16, 1
	v_add3_u32 v16, v7, v16, s64
	ds_write_b16_d16_hi v66, v16 offset:2448
	v_min_f32_e64 v16, -v57, s66
	v_mul_f32_e32 v16, 0x3fb8aa3b, v16
	v_exp_f32_e32 v16, v16
	v_mul_f32_e32 v7, v7, v65
	v_bfe_u32 v67, v7, 16, 1
	v_add3_u32 v7, v7, v67, s64
	ds_write_b16_d16_hi v66, v7 offset:19856
	v_mul_f32_e32 v7, v33, v16
	v_mul_f32_e32 v16, 0x3fb8aa3b, v58
	v_exp_f32_e32 v16, v16
	v_bfe_u32 v67, v7, 16, 1
	v_add3_u32 v7, v7, v67, s64
	ds_write_b16_d16_hi v6, v7 offset:37264
	v_mul_f32_e32 v7, v16, v78
	v_bfe_u32 v16, v7, 16, 1
	v_add3_u32 v16, v7, v16, s64
	ds_write_b16_d16_hi v66, v16 offset:2720
	v_min_f32_e64 v16, -v58, s66
	v_mul_f32_e32 v16, 0x3fb8aa3b, v16
	v_exp_f32_e32 v16, v16
	v_mul_f32_e32 v7, v7, v65
	v_bfe_u32 v67, v7, 16, 1
	v_add3_u32 v7, v7, v67, s64
	ds_write_b16_d16_hi v66, v7 offset:20128
	v_mul_f32_e32 v7, v34, v16
	v_mul_f32_e32 v16, 0x3fb8aa3b, v59
	v_exp_f32_e32 v16, v16
	v_bfe_u32 v67, v7, 16, 1
	v_add3_u32 v7, v7, v67, s64
	ds_write_b16_d16_hi v6, v7 offset:37536
	v_mul_f32_e32 v7, v16, v79
	v_bfe_u32 v16, v7, 16, 1
	v_add3_u32 v16, v7, v16, s64
	ds_write_b16_d16_hi v66, v16 offset:2992
	v_min_f32_e64 v16, -v59, s66
	v_mul_f32_e32 v16, 0x3fb8aa3b, v16
	v_exp_f32_e32 v16, v16
	v_mul_f32_e32 v7, v7, v65
	v_bfe_u32 v67, v7, 16, 1
	v_add3_u32 v7, v7, v67, s64
	ds_write_b16_d16_hi v66, v7 offset:20400
	v_mul_f32_e32 v7, v38, v16
	v_mul_f32_e32 v16, 0x3fb8aa3b, v60
	v_exp_f32_e32 v16, v16
	v_bfe_u32 v67, v7, 16, 1
	v_add3_u32 v7, v7, v67, s64
	ds_write_b16_d16_hi v6, v7 offset:37808
	v_mul_f32_e32 v7, v16, v80
	v_bfe_u32 v16, v7, 16, 1
	v_add3_u32 v16, v7, v16, s64
	ds_write_b16_d16_hi v66, v16 offset:3264
	v_min_f32_e64 v16, -v60, s66
	v_mul_f32_e32 v16, 0x3fb8aa3b, v16
	v_exp_f32_e32 v16, v16
	v_mul_f32_e32 v7, v7, v65
	v_bfe_u32 v67, v7, 16, 1
	v_add3_u32 v7, v7, v67, s64
	ds_write_b16_d16_hi v66, v7 offset:20672
	v_mul_f32_e32 v7, v40, v16
	v_mul_f32_e32 v16, 0x3fb8aa3b, v61
	v_exp_f32_e32 v16, v16
	v_bfe_u32 v67, v7, 16, 1
	v_add3_u32 v7, v7, v67, s64
	ds_write_b16_d16_hi v6, v7 offset:38080
	v_mul_f32_e32 v7, v16, v81
	v_bfe_u32 v16, v7, 16, 1
	v_add3_u32 v16, v7, v16, s64
	ds_write_b16_d16_hi v66, v16 offset:3536
	v_min_f32_e64 v16, -v61, s66
	v_mul_f32_e32 v16, 0x3fb8aa3b, v16
	v_exp_f32_e32 v16, v16
	v_mul_f32_e32 v7, v7, v65
	v_bfe_u32 v67, v7, 16, 1
	v_add3_u32 v7, v7, v67, s64
	ds_write_b16_d16_hi v66, v7 offset:20944
	v_mul_f32_e32 v7, v42, v16
	v_mul_f32_e32 v16, 0x3fb8aa3b, v62
	v_exp_f32_e32 v16, v16
	v_bfe_u32 v67, v7, 16, 1
	v_add3_u32 v7, v7, v67, s64
	ds_write_b16_d16_hi v6, v7 offset:38352
	v_mul_f32_e32 v7, v16, v82
	v_bfe_u32 v16, v7, 16, 1
	v_add3_u32 v16, v7, v16, s64
	ds_write_b16_d16_hi v66, v16 offset:3808
	v_min_f32_e64 v16, -v62, s66
	v_mul_f32_e32 v16, 0x3fb8aa3b, v16
	v_exp_f32_e32 v16, v16
	v_mul_f32_e32 v7, v7, v65
	v_bfe_u32 v67, v7, 16, 1
	v_add3_u32 v7, v7, v67, s64
	ds_write_b16_d16_hi v66, v7 offset:21216
	v_mul_f32_e32 v7, v44, v16
	v_mul_f32_e32 v16, 0x3fb8aa3b, v63
	v_exp_f32_e32 v16, v16
	v_bfe_u32 v67, v7, 16, 1
	v_add3_u32 v7, v7, v67, s64
	ds_write_b16_d16_hi v6, v7 offset:38624
	v_mul_f32_e32 v7, v16, v64
	v_bfe_u32 v16, v7, 16, 1
	v_add3_u32 v16, v7, v16, s64
	ds_write_b16_d16_hi v66, v16 offset:4080
	v_min_f32_e64 v16, -v63, s66
	v_mul_f32_e32 v16, 0x3fb8aa3b, v16
	v_exp_f32_e32 v16, v16
	v_mul_f32_e32 v7, v7, v65
	v_bfe_u32 v64, v7, 16, 1
	v_add3_u32 v7, v7, v64, s64
	ds_write_b16_d16_hi v66, v7 offset:21488
	v_mul_f32_e32 v7, v51, v16
	v_bfe_u32 v16, v7, 16, 1
	v_add3_u32 v7, v7, v16, s64
	v_cmp_gt_i32_e32 vcc, 3, v2
	ds_write_b16_d16_hi v6, v7 offset:38896
	s_and_saveexec_b64 s[36:37], vcc
	s_cbranch_execz .LBB0_801
	v_cmp_gt_i32_e32 vcc, 1, v2
	v_add_f32_e32 v5, 0, v5
	v_cmp_ne_u32_e64 s[4:5], 2, v2
	v_sub_f32_e32 v6, v63, v37
	v_sub_f32_e32 v7, v63, v39
	v_sub_f32_e32 v16, v63, v41
	v_sub_f32_e32 v37, v63, v43
	v_sub_f32_e32 v39, v63, v49
	v_sub_f32_e32 v41, v63, v53
	v_sub_f32_e32 v43, v63, v54
	v_sub_f32_e32 v49, v63, v55
	v_sub_f32_e32 v53, v63, v56
	v_sub_f32_e32 v54, v63, v57
	v_sub_f32_e32 v55, v63, v58
	v_sub_f32_e32 v56, v63, v59
	v_sub_f32_e32 v57, v63, v60
	v_sub_f32_e32 v58, v63, v61
	v_sub_f32_e32 v59, v63, v62
	v_sub_f32_e32 v60, v63, v63
	s_mov_b64 s[38:39], 0
	v_mov_b32_e32 v61, v2

.LBB0_801:
	s_or_b64 exec, exec, s[36:37]
	v_lshlrev_b32_e32 v2, 16, v9
	v_or_b32_sdwa v4, v2, v1 dst_sel:DWORD dst_unused:UNUSED_PAD src0_sel:DWORD src1_sel:WORD_0
	v_lshlrev_b32_e32 v1, 16, v8
	s_waitcnt vmcnt(4)
	v_or_b32_sdwa v5, v1, v50 dst_sel:DWORD dst_unused:UNUSED_PAD src0_sel:DWORD src1_sel:WORD_0
	v_lshlrev_b32_e32 v1, 16, v13
	v_or_b32_sdwa v6, v1, v12 dst_sel:DWORD dst_unused:UNUSED_PAD src0_sel:DWORD src1_sel:WORD_0
	v_lshlrev_b32_e32 v1, 16, v26
	s_waitcnt vmcnt(3)
	v_or_b32_sdwa v7, v1, v48 dst_sel:DWORD dst_unused:UNUSED_PAD src0_sel:DWORD src1_sel:WORD_0
	v_lshlrev_b32_e32 v1, 16, v19
	v_or_b32_sdwa v8, v1, v18 dst_sel:DWORD dst_unused:UNUSED_PAD src0_sel:DWORD src1_sel:WORD_0
	v_lshlrev_b32_e32 v1, 16, v30
	s_waitcnt vmcnt(2)
	v_or_b32_sdwa v9, v1, v46 dst_sel:DWORD dst_unused:UNUSED_PAD src0_sel:DWORD src1_sel:WORD_0
	v_lshlrev_b32_e32 v1, 16, v36
	v_or_b32_sdwa v10, v1, v35 dst_sel:DWORD dst_unused:UNUSED_PAD src0_sel:DWORD src1_sel:WORD_0
	s_waitcnt vmcnt(0)
	v_lshlrev_b32_e32 v1, 16, v47
	v_or_b32_sdwa v11, v1, v45 dst_sel:DWORD dst_unused:UNUSED_PAD src0_sel:DWORD src1_sel:WORD_0
	v_mul_u32_u24_e32 v1, 0x90, v3
	v_lshlrev_b32_e32 v0, 1, v0
	v_and_b32_e32 v27, 15, v25
	v_bfe_u32 v28, v25, 4, 2
	v_add3_u32 v0, s69, v1, v0
	v_bfe_u32 v29, v25, 6, 2
	v_ashrrev_i32_e32 v30, 8, v25
	ds_write_b128 v0, v[4:7]
	ds_write_b128 v0, v[8:11] offset:16
	ds_write_b128 v96, v[160:163]
	ds_write_b128 v96, v[164:167] offset:8704
	ds_write_b128 v96, v[168:171] offset:17408
	ds_write_b128 v96, v[172:175] offset:26112
	v_lshl_add_u32 v4, v28, 4, 0
	v_lshlrev_b32_e32 v26, 2, v28
	v_cmp_le_i32_e32 vcc, v29, v30
	v_lshl_or_b32 v7, v30, 4, v27
	s_waitcnt lgkmcnt(0)
	s_barrier
	s_and_saveexec_b64 s[4:5], vcc
	s_xor_b64 s[4:5], exec, s[4:5]
	s_cbranch_execz .LBB0_805
	v_mad_i32_i24 v0, v30, v30, v30
	v_lshrrev_b32_e32 v0, 1, v0
	v_add_u32_e32 v0, v0, v29
	v_lshl_or_b32 v0, v0, 4, v27
	v_mad_u64_u32 v[6:7], s[6:7], v0, s70, v[4:5]
	ds_read_b128 v[0:3], v6 offset:34816
	v_lshl_or_b32 v7, v30, 4, v27
	v_mad_u64_u32 v[18:19], s[6:7], v7, s70, v[4:5]
	ds_read_b128 v[8:11], v6 offset:34880
	ds_read_b128 v[12:15], v18
	ds_read_b128 v[32:35], v18 offset:64
	v_cmp_eq_u32_e32 vcc, v30, v29
	s_waitcnt lgkmcnt(1)
	v_mfma_f32_16x16x32_bf16 v[0:3], v[0:3], v[12:15], 0
	ds_read_b128 v[12:15], v6 offset:34944
	ds_read_b128 v[36:39], v6 offset:35008
	s_waitcnt lgkmcnt(2)
	v_mfma_f32_16x16x32_bf16 v[0:3], v[8:11], v[32:35], v[0:3]
	ds_read_b128 v[8:11], v18 offset:128
	ds_read_b128 v[32:35], v18 offset:192
	s_waitcnt lgkmcnt(1)
	v_mfma_f32_16x16x32_bf16 v[0:3], v[12:15], v[8:11], v[0:3]
	s_waitcnt lgkmcnt(0)
	v_mfma_f32_16x16x32_bf16 v[0:3], v[36:39], v[32:35], v[0:3]
	s_and_saveexec_b64 s[6:7], vcc
	s_cbranch_execz .LBB0_804
	v_mov_b32_e32 v6, s29
	v_cmp_gt_u32_e32 vcc, v26, v27
	s_nop 3
	v_cndmask_b32_e32 v5, v0, v6, vcc
	v_cmp_lt_u32_e32 vcc, v26, v27
	s_nop 1
	v_cndmask_b32_e32 v0, v5, v0, vcc
	v_or_b32_e32 v5, 2, v26
	v_cndmask_b32_e32 v1, 0, v1, vcc
	v_cmp_le_u32_e32 vcc, v5, v27
	v_or_b32_e32 v5, 3, v26
	s_nop 0
	v_cndmask_b32_e32 v2, 0, v2, vcc
	v_cmp_le_u32_e32 vcc, v5, v27
	s_nop 1
	v_cndmask_b32_e32 v3, 0, v3, vcc

.LBB0_811:
	s_andn2_saveexec_b64 s[4:5], s[4:5]
	s_nop 3
	v_mov_b32_e32 v0, 0
	v_mov_b32_e32 v1, v0
	v_mov_b32_e32 v2, v0
	v_mov_b32_e32 v3, v0
	s_or_b64 exec, exec, s[4:5]
	v_bfe_u32 v4, v0, 16, 1
	v_add3_u32 v0, v0, v4, s64
	v_bfe_u32 v4, v1, 16, 1
	v_lshrrev_b32_e32 v0, 16, v0
	v_add3_u32 v1, v1, v4, s64
	v_and_or_b32 v0, v1, s72, v0
	v_bfe_u32 v1, v2, 16, 1
	v_add3_u32 v1, v2, v1, s64
	v_bfe_u32 v2, v3, 16, 1
	v_lshrrev_b32_e32 v1, 16, v1
	v_add3_u32 v2, v3, v2, s64
	v_and_or_b32 v1, v2, s72, v1
	v_mad_u64_u32 v[2:3], s[4:5], v7, s68, v[6:7]
	s_ashr_i32 s15, s14, 31
	v_lshlrev_b32_e32 v18, 6, v30
	s_lshl_b64 s[4:5], s[14:15], 7
	v_or_b32_e32 v50, s4, v27
	v_mov_b32_e32 v51, s5
	v_ashrrev_i32_e32 v19, 31, v18
	ds_write_b64 v2, v[0:1]
	v_lshlrev_b32_e32 v16, 1, v5
	v_lshl_add_u64 v[0:1], v[50:51], 0, v[18:19]
	v_lshl_add_u64 v[52:53], s[16:17], 0, v[16:17]
	v_lshlrev_b64 v[0:1], 8, v[0:1]
	v_lshl_add_u64 v[42:43], v[52:53], 0, v[0:1]
	s_waitcnt lgkmcnt(0)
	s_barrier
	v_lshl_or_b32 v32, v29, 4, v27
	v_mad_u32_u24 v31, v32, s70, 0
	ds_read_b128 v[184:187], v102
	ds_read_b128 v[188:191], v102 offset:64
	ds_read_b128 v[192:195], v103
	ds_read_b128 v[196:199], v103 offset:64
	ds_read_b128 v[200:203], v103 offset:128
	ds_read_b128 v[204:207], v103 offset:192
	ds_read_b128 v[104:107], v101
	ds_read_b128 v[108:111], v101 offset:64
	ds_read_b128 v[112:115], v100
	ds_read_b128 v[116:119], v100 offset:64
	ds_read_b128 v[120:123], v100 offset:128
	ds_read_b128 v[124:127], v100 offset:192
	s_waitcnt lgkmcnt(6)
	ds_read_b128 v[128:131], v101 offset:2304
	ds_read_b128 v[132:135], v101 offset:2368
	ds_read_b128 v[136:139], v100 offset:4352
	ds_read_b128 v[140:143], v100 offset:4416
	ds_read_b128 v[144:147], v100 offset:4480
	ds_read_b128 v[148:151], v100 offset:4544
	s_waitcnt lgkmcnt(6)
	v_mfma_f32_16x16x32_bf16 v[12:15], v[104:107], v[184:187], 0
	v_mfma_f32_16x16x32_bf16 v[12:15], v[108:111], v[188:191], v[12:15]
	v_mfma_f32_16x16x32_bf16 v[12:15], v[112:115], v[192:195], v[12:15]
	v_mfma_f32_16x16x32_bf16 v[12:15], v[116:119], v[196:199], v[12:15]
	v_mfma_f32_16x16x32_bf16 v[12:15], v[120:123], v[200:203], v[12:15]
	v_mfma_f32_16x16x32_bf16 v[12:15], v[124:127], v[204:207], v[12:15]
	ds_read_b128 v[104:107], v101 offset:4608
	ds_read_b128 v[108:111], v101 offset:4672
	ds_read_b128 v[112:115], v100 offset:8704
	ds_read_b128 v[116:119], v100 offset:8768
	ds_read_b128 v[120:123], v100 offset:8832
	ds_read_b128 v[124:127], v100 offset:8896
	s_waitcnt lgkmcnt(6)
	v_mfma_f32_16x16x32_bf16 v[8:11], v[128:131], v[184:187], 0
	v_mfma_f32_16x16x32_bf16 v[8:11], v[132:135], v[188:191], v[8:11]
	v_mfma_f32_16x16x32_bf16 v[8:11], v[136:139], v[192:195], v[8:11]
	v_mfma_f32_16x16x32_bf16 v[8:11], v[140:143], v[196:199], v[8:11]
	v_mfma_f32_16x16x32_bf16 v[8:11], v[144:147], v[200:203], v[8:11]
	v_mfma_f32_16x16x32_bf16 v[8:11], v[148:151], v[204:207], v[8:11]
	ds_read_b128 v[128:131], v101 offset:6912
	ds_read_b128 v[132:135], v101 offset:6976
	ds_read_b128 v[136:139], v100 offset:13056
	ds_read_b128 v[140:143], v100 offset:13120
	ds_read_b128 v[144:147], v100 offset:13184
	ds_read_b128 v[148:151], v100 offset:13248
	s_waitcnt lgkmcnt(6)
	v_mfma_f32_16x16x32_bf16 v[4:7], v[104:107], v[184:187], 0
	v_mfma_f32_16x16x32_bf16 v[4:7], v[108:111], v[188:191], v[4:7]
	v_mfma_f32_16x16x32_bf16 v[4:7], v[112:115], v[192:195], v[4:7]
	v_mfma_f32_16x16x32_bf16 v[4:7], v[116:119], v[196:199], v[4:7]
	v_mfma_f32_16x16x32_bf16 v[4:7], v[120:123], v[200:203], v[4:7]
	v_mfma_f32_16x16x32_bf16 v[4:7], v[124:127], v[204:207], v[4:7]
	s_waitcnt lgkmcnt(0)
	v_mfma_f32_16x16x32_bf16 v[0:3], v[128:131], v[184:187], 0
	v_mfma_f32_16x16x32_bf16 v[0:3], v[132:135], v[188:191], v[0:3]
	v_mfma_f32_16x16x32_bf16 v[0:3], v[136:139], v[192:195], v[0:3]
	v_mfma_f32_16x16x32_bf16 v[0:3], v[140:143], v[196:199], v[0:3]
	v_mfma_f32_16x16x32_bf16 v[0:3], v[144:147], v[200:203], v[0:3]
	v_mfma_f32_16x16x32_bf16 v[0:3], v[148:151], v[204:207], v[0:3]
	v_mul_f32_e32 v16, v13, v13
	v_mul_f32_e32 v19, v9, v9
	v_fmac_f32_e32 v16, v12, v12
	v_fmac_f32_e32 v19, v8, v8
	v_fmac_f32_e32 v16, v14, v14
	v_fmac_f32_e32 v19, v10, v10
	v_fmac_f32_e32 v16, v15, v15
	v_fmac_f32_e32 v19, v11, v11
	v_add_f32_e32 v16, v16, v19
	v_mul_f32_e32 v19, v5, v5
	v_fmac_f32_e32 v19, v4, v4
	v_fmac_f32_e32 v19, v6, v6
	v_fmac_f32_e32 v19, v7, v7
	v_add_f32_e32 v16, v16, v19
	v_mul_f32_e32 v19, v1, v1
	v_fmac_f32_e32 v19, v0, v0
	v_fmac_f32_e32 v19, v2, v2
	v_fmac_f32_e32 v19, v3, v3
	v_add_f32_e32 v16, v16, v19
	ds_bpermute_b32 v19, v22, v16
	v_cmp_eq_u32_e32 vcc, 0, v28
	s_waitcnt lgkmcnt(0)
	v_add_f32_e32 v16, v16, v19
	ds_bpermute_b32 v19, v23, v16
	s_and_saveexec_b64 s[4:5], vcc
	s_cbranch_execz .LBB0_797
	v_lshl_add_u32 v28, v29, 7, s73
	v_lshlrev_b32_e32 v27, 3, v27
	v_lshlrev_b32_e32 v29, 2, v30
	v_add3_u32 v27, v28, v27, v29
	s_waitcnt lgkmcnt(0)
	v_add_f32_e32 v16, v16, v19
	ds_write_b32 v27, v16
	s_branch .LBB0_797

.LBB0_816:
	s_andn2_b64 vcc, exec, s[4:5]
	s_cbranch_vccnz .LBB0_865
	s_and_b32 s2, s94, 7
	s_mov_b64 s[4:5], s[0:1]
	s_load_dwordx4 s[12:15], s[4:5], 0xd8
	v_mov_b32_e32 v10, v156
	s_waitcnt lgkmcnt(0)
	s_add_u32 s6, s14, 0x2030000
	s_addc_u32 s7, s15, 0
	s_cmp_lt_i32 s2, 8
	s_cselect_b64 s[8:9], -1, 0
	s_ashr_i32 s3, s2, 2
	s_add_i32 s3, s3, 64
	s_and_b32 s10, s2, 3
	v_readfirstlane_b32 s22, v10
	s_cmp_gt_i32 s2, 7
	s_mul_hi_i32 s11, s3, 0x3c0000
	s_mul_i32 s33, s3, 0x3c0000
	s_cbranch_scc1 .LBB0_833
	s_lshr_b32 s98, s94, 3
	s_cmp_lg_u32 s98, 0
	s_cbranch_scc1 .LBB0_833
	v_lshlrev_b32_e32 v0, 4, v10
	v_add_u32_e32 v1, 0x2000, v0
	v_ashrrev_i32_e32 v2, 31, v1
	v_lshrrev_b32_e32 v2, 22, v2
	v_add_u32_e32 v2, v1, v2
	v_ashrrev_i32_e32 v9, 10, v2
	v_lshlrev_b32_e32 v2, 5, v9
	v_and_b32_e32 v8, 32, v2
	v_mul_i32_i24_e32 v2, 0x400, v9
	v_sub_u32_e32 v1, v1, v2
	v_lshrrev_b32_e32 v2, 4, v1
	v_bitop3_b32 v1, v2, v1, 32 bitop3:0x6c
	v_ashrrev_i32_e32 v2, 31, v1
	v_lshrrev_b32_e32 v2, 26, v2
	v_add_u32_e32 v2, v1, v2
	v_ashrrev_i32_e32 v11, 6, v2
	v_and_b32_e32 v2, 0xc0, v2
	v_sub_u32_e32 v1, v1, v2
	v_mov_b32_e32 v2, 1
	v_lshlrev_b32_e32 v3, 3, v9
	v_ashrrev_i16_sdwa v1, v2, sext(v1) dst_sel:DWORD dst_unused:UNUSED_PAD src0_sel:DWORD src1_sel:BYTE_0
	v_and_b32_e32 v3, -16, v3
	v_bfe_i32 v12, v1, 0, 16
	v_add_u32_e32 v3, v11, v3
	s_movk_i32 s24, 0x1e00
	v_add_u32_e32 v1, v8, v12
	v_lshlrev_b32_e32 v4, 10, v3
	v_mul_lo_u32 v3, v3, s24
	v_lshl_add_u32 v128, v1, 1, v4
	v_add_lshl_u32 v130, v1, v3, 1
	v_ashrrev_i32_e32 v1, 31, v10
	v_lshrrev_b32_e32 v1, 26, v1
	v_add_u32_e32 v1, v10, v1
	v_ashrrev_i32_e32 v14, 6, v1
	v_lshlrev_b32_e32 v1, 5, v14
	v_and_b32_e32 v13, 32, v1
	v_bfe_i32 v1, v10, 27, 1
	v_lshrrev_b32_e32 v1, 22, v1
	v_add_u32_e32 v1, v0, v1
	v_and_b32_e32 v1, 0xfffffc00, v1
	v_sub_u32_e32 v0, v0, v1
	v_lshrrev_b32_e32 v1, 4, v0
	v_bitop3_b32 v0, v1, v0, 32 bitop3:0x6c
	v_ashrrev_i32_e32 v1, 31, v0
	v_lshrrev_b32_e32 v1, 26, v1
	s_ashr_i32 s18, s22, 6
	v_add_u32_e32 v1, v0, v1
	s_ashr_i32 s23, s22, 8
	s_lshl_b32 s26, s18, 10
	v_ashrrev_i32_e32 v15, 6, v1
	v_and_b32_e32 v1, 0xc0, v1
	s_lshl_b32 s4, s10, 18
	v_sub_u32_e32 v0, v0, v1
	v_lshlrev_b32_e32 v1, 3, v14
	s_add_u32 s16, s14, s4
	v_ashrrev_i16_sdwa v0, v2, sext(v0) dst_sel:DWORD dst_unused:UNUSED_PAD src0_sel:DWORD src1_sel:BYTE_0
	v_and_b32_e32 v1, -16, v1
	s_addc_u32 s17, s15, 0
	v_bfe_i32 v16, v0, 0, 16
	v_add_u32_e32 v1, v15, v1
	s_add_u32 s4, s16, 0x1100000
	v_add_u32_e32 v0, v13, v16
	v_lshlrev_b32_e32 v2, 10, v1
	s_addc_u32 s5, s17, 0
	s_add_i32 s42, s26, 0
	v_lshl_add_u32 v132, v0, 1, v2
	s_add_i32 m0, s42, 0x10000
	v_mul_lo_u32 v1, v1, s24
	global_load_lds_dwordx4 v132, s[4:5]
	s_add_i32 m0, s42, 0x12000
	s_add_u32 s16, s16, 0x1120000
	global_load_lds_dwordx4 v128, s[4:5]
	s_addc_u32 s17, s17, 0
	s_add_i32 m0, s42, 0x14000
	v_add_lshl_u32 v134, v0, v1, 1
	global_load_lds_dwordx4 v132, s[16:17]
	s_add_i32 m0, s42, 0x16000
	s_add_u32 s30, s6, s33
	s_addc_u32 s31, s7, s11
	s_add_i32 s43, s42, 0x2000
	global_load_lds_dwordx4 v128, s[16:17]
	s_mov_b32 m0, s42
	s_add_u32 s16, s30, 0x1e0000
	global_load_lds_dwordx4 v134, s[30:31]
	s_mov_b32 m0, s43
	s_addc_u32 s17, s31, 0
	s_add_i32 s46, s42, 0x4000
	global_load_lds_dwordx4 v130, s[30:31]
	s_mov_b32 m0, s46
	s_add_i32 s47, s42, 0x6000
	global_load_lds_dwordx4 v134, s[16:17]
	s_mov_b32 m0, s47
	v_mov_b32_e32 v137, 0
	global_load_lds_dwordx4 v130, s[16:17]
	v_mov_b32_e32 v133, v137
	v_mov_b32_e32 v129, v137
	v_mov_b32_e32 v135, v137
	v_mov_b32_e32 v131, v137
	s_cmp_eq_u32 s23, 1
	s_mov_b32 s48, 0
	s_waitcnt vmcnt(0)
	v_lshl_add_u64 v[6:7], s[4:5], 0, v[132:133]
	v_lshl_add_u64 v[4:5], s[4:5], 0, v[128:129]
	v_lshl_add_u64 v[0:1], s[30:31], 0, v[134:135]
	s_cselect_b64 s[16:17], -1, 0
	s_cmp_lg_u32 s23, 1
	v_lshl_add_u64 v[2:3], s[30:31], 0, v[130:131]
	s_cbranch_scc1 .LBB0_820
	s_barrier

.LBB0_829:
	s_lshr_b32 s98, s94, 2
	s_and_b32 s98, s98, 1
	s_add_i32 s98, s98, 64
	s_and_b32 s99, s94, 3
	v_writelane_b32 v214, s98, 0
	v_writelane_b32 v214, s99, 1
	s_movk_i32 s98, 0x0
	v_writelane_b32 v214, s98, 2
	s_branch .Lepi_merge
.Lepi_ret_0:
	s_waitcnt vmcnt(0)
	s_barrier
	v_readfirstlane_b32 s100, v156
	s_cmp_lt_u32 s100, 64
	s_cbranch_scc0 .Lflags_0
	buffer_wbl2 sc1
	s_waitcnt vmcnt(0)
	s_and_b32 s98, s94, 7
	s_lshl_b32 s98, s98, 6
	s_add_u32 s98, s98, 0x13fb3800
	s_add_u32 s98, s40, s98
	s_addc_u32 s99, s41, 0
	v_mov_b32_e32 v213, 0
	v_mov_b32_e32 v212, 1
	s_mov_b64 s[100:101], exec
	s_mov_b64 exec, 1
	global_atomic_add v213, v212, s[98:99] sc1
	s_mov_b64 exec, s[100:101]
	s_waitcnt vmcnt(0)

.LBB0_833:
	v_mov_b32_e32 v10, v156
	v_cndmask_b32_e64 v0, 0, 1, s[8:9]
	v_cmp_ne_u32_e64 s[4:5], 1, v0
	s_andn2_b64 vcc, exec, s[8:9]
	v_readfirstlane_b32 s22, v10
	s_cbranch_vccnz .LBB0_849
	s_lshr_b32 s98, s94, 3
	s_cmp_lg_u32 s98, 1
	s_cbranch_scc1 .LBB0_849
	v_lshlrev_b32_e32 v0, 4, v10
	v_add_u32_e32 v1, 0x2000, v0
	v_ashrrev_i32_e32 v2, 31, v1
	v_lshrrev_b32_e32 v2, 22, v2
	v_add_u32_e32 v2, v1, v2
	v_ashrrev_i32_e32 v9, 10, v2
	v_lshlrev_b32_e32 v2, 5, v9
	v_and_b32_e32 v8, 32, v2
	v_mul_i32_i24_e32 v2, 0x400, v9
	v_sub_u32_e32 v1, v1, v2
	v_lshrrev_b32_e32 v2, 4, v1
	v_bitop3_b32 v1, v2, v1, 32 bitop3:0x6c
	v_ashrrev_i32_e32 v2, 31, v1
	v_lshrrev_b32_e32 v2, 26, v2
	v_add_u32_e32 v2, v1, v2
	v_ashrrev_i32_e32 v11, 6, v2
	v_and_b32_e32 v2, 0xc0, v2
	v_sub_u32_e32 v1, v1, v2
	v_mov_b32_e32 v2, 1
	v_lshlrev_b32_e32 v3, 3, v9
	v_ashrrev_i16_sdwa v1, v2, sext(v1) dst_sel:DWORD dst_unused:UNUSED_PAD src0_sel:DWORD src1_sel:BYTE_0
	v_and_b32_e32 v3, -16, v3
	v_bfe_i32 v12, v1, 0, 16
	v_add_u32_e32 v3, v11, v3
	s_movk_i32 s24, 0x1e00
	v_add_u32_e32 v1, v8, v12
	v_lshlrev_b32_e32 v4, 10, v3
	v_mul_lo_u32 v3, v3, s24
	v_lshl_add_u32 v128, v1, 1, v4
	v_add_lshl_u32 v130, v1, v3, 1
	v_ashrrev_i32_e32 v1, 31, v10
	v_lshrrev_b32_e32 v1, 26, v1
	v_add_u32_e32 v1, v10, v1
	v_ashrrev_i32_e32 v14, 6, v1
	v_lshlrev_b32_e32 v1, 5, v14
	v_and_b32_e32 v13, 32, v1
	v_bfe_i32 v1, v10, 27, 1
	v_lshrrev_b32_e32 v1, 22, v1
	v_add_u32_e32 v1, v0, v1
	v_and_b32_e32 v1, 0xfffffc00, v1
	v_sub_u32_e32 v0, v0, v1
	v_lshrrev_b32_e32 v1, 4, v0
	v_bitop3_b32 v0, v1, v0, 32 bitop3:0x6c
	v_ashrrev_i32_e32 v1, 31, v0
	s_add_u32 s42, s14, 0x2031000
	v_lshrrev_b32_e32 v1, 26, v1
	s_addc_u32 s43, s15, 0
	s_ashr_i32 s18, s22, 6
	v_add_u32_e32 v1, v0, v1
	s_ashr_i32 s23, s22, 8
	s_lshl_b32 s26, s18, 10
	v_ashrrev_i32_e32 v15, 6, v1
	v_and_b32_e32 v1, 0xc0, v1
	s_lshl_b32 s8, s10, 18
	v_sub_u32_e32 v0, v0, v1
	v_lshlrev_b32_e32 v1, 3, v14
	s_add_u32 s16, s14, s8
	v_ashrrev_i16_sdwa v0, v2, sext(v0) dst_sel:DWORD dst_unused:UNUSED_PAD src0_sel:DWORD src1_sel:BYTE_0
	v_and_b32_e32 v1, -16, v1
	s_addc_u32 s17, s15, 0
	v_bfe_i32 v16, v0, 0, 16
	v_add_u32_e32 v1, v15, v1
	s_add_u32 s8, s16, 0x1200000
	v_add_u32_e32 v0, v13, v16
	v_lshlrev_b32_e32 v2, 10, v1
	s_addc_u32 s9, s17, 0
	s_add_i32 s46, s26, 0
	v_lshl_add_u32 v132, v0, 1, v2
	s_add_i32 m0, s46, 0x10000
	v_mul_lo_u32 v1, v1, s24
	global_load_lds_dwordx4 v132, s[8:9]
	s_add_i32 m0, s46, 0x12000
	s_add_u32 s16, s16, 0x1220000
	global_load_lds_dwordx4 v128, s[8:9]
	s_addc_u32 s17, s17, 0
	s_add_i32 m0, s46, 0x14000
	v_add_lshl_u32 v134, v0, v1, 1
	global_load_lds_dwordx4 v132, s[16:17]
	s_add_i32 m0, s46, 0x16000
	s_add_u32 s30, s42, s33
	s_addc_u32 s31, s43, s11
	s_add_i32 s47, s46, 0x2000
	global_load_lds_dwordx4 v128, s[16:17]
	s_mov_b32 m0, s46
	s_add_u32 s16, s30, 0x1e0000
	global_load_lds_dwordx4 v134, s[30:31]
	s_mov_b32 m0, s47
	s_addc_u32 s17, s31, 0
	s_add_i32 s48, s46, 0x4000
	global_load_lds_dwordx4 v130, s[30:31]
	s_mov_b32 m0, s48
	s_add_i32 s49, s46, 0x6000
	global_load_lds_dwordx4 v134, s[16:17]
	s_mov_b32 m0, s49
	v_mov_b32_e32 v137, 0
	global_load_lds_dwordx4 v130, s[16:17]
	v_mov_b32_e32 v133, v137
	v_mov_b32_e32 v129, v137
	v_mov_b32_e32 v135, v137
	v_mov_b32_e32 v131, v137
	s_cmp_eq_u32 s23, 1
	s_mov_b32 s50, 0
	s_waitcnt vmcnt(0)
	v_lshl_add_u64 v[6:7], s[8:9], 0, v[132:133]
	v_lshl_add_u64 v[4:5], s[8:9], 0, v[128:129]
	v_lshl_add_u64 v[0:1], s[30:31], 0, v[134:135]
	s_cselect_b64 s[16:17], -1, 0
	s_cmp_lg_u32 s23, 1
	v_lshl_add_u64 v[2:3], s[30:31], 0, v[130:131]
	s_cbranch_scc1 .LBB0_836
	s_barrier

.LBB0_845:
	s_lshr_b32 s98, s94, 2
	s_and_b32 s98, s98, 1
	s_add_i32 s98, s98, 64
	s_and_b32 s99, s94, 3
	v_writelane_b32 v214, s98, 0
	v_writelane_b32 v214, s99, 1
	s_movk_i32 s98, 0x11
	v_writelane_b32 v214, s98, 2
	s_and_b32 s98, s94, 7
	s_lshl_b32 s98, s98, 6
	s_add_u32 s98, s98, 0x13fb3800
	s_add_u32 s98, s40, s98
	s_addc_u32 s99, s41, 0
	v_mov_b32_e32 v213, 0
.Lflagw_1:
	global_load_dword v212, v213, s[98:99] sc1
	s_waitcnt vmcnt(0)
	v_readfirstlane_b32 s100, v212
	s_cmp_ge_u32 s100, 1
	s_cbranch_scc1 .Lflagd_1
	s_sleep 2
	s_branch .Lflagw_1
.Lflagd_1:
	buffer_inv sc1
	s_waitcnt vmcnt(0)
	s_branch .Lepi_merge

.LBB0_849:
	v_mov_b32_e32 v10, v156
	s_and_b64 vcc, exec, s[4:5]
	v_readfirstlane_b32 s18, v10
	s_cbranch_vccnz .LBB0_865
	s_lshr_b32 s98, s94, 3
	s_cmp_lg_u32 s98, 2
	s_cbranch_scc1 .LBB0_865
	v_lshlrev_b32_e32 v0, 4, v10
	v_add_u32_e32 v1, 0x2000, v0
	v_ashrrev_i32_e32 v2, 31, v1
	v_lshrrev_b32_e32 v2, 22, v2
	v_add_u32_e32 v2, v1, v2
	v_ashrrev_i32_e32 v9, 10, v2
	v_lshlrev_b32_e32 v2, 5, v9
	v_and_b32_e32 v8, 32, v2
	v_mul_i32_i24_e32 v2, 0x400, v9
	v_sub_u32_e32 v1, v1, v2
	v_lshrrev_b32_e32 v2, 4, v1
	v_bitop3_b32 v1, v2, v1, 32 bitop3:0x6c
	v_ashrrev_i32_e32 v2, 31, v1
	v_lshrrev_b32_e32 v2, 26, v2
	v_add_u32_e32 v2, v1, v2
	v_ashrrev_i32_e32 v11, 6, v2
	v_and_b32_e32 v2, 0xc0, v2
	v_sub_u32_e32 v1, v1, v2
	v_mov_b32_e32 v2, 1
	v_lshlrev_b32_e32 v3, 3, v9
	v_ashrrev_i16_sdwa v1, v2, sext(v1) dst_sel:DWORD dst_unused:UNUSED_PAD src0_sel:DWORD src1_sel:BYTE_0
	v_and_b32_e32 v3, -16, v3
	v_bfe_i32 v12, v1, 0, 16
	v_add_u32_e32 v3, v11, v3
	s_movk_i32 s23, 0x1e00
	v_add_u32_e32 v1, v8, v12
	v_lshlrev_b32_e32 v4, 10, v3
	v_mul_lo_u32 v3, v3, s23
	v_lshl_add_u32 v128, v1, 1, v4
	v_add_lshl_u32 v130, v1, v3, 1
	v_ashrrev_i32_e32 v1, 31, v10
	v_lshrrev_b32_e32 v1, 26, v1
	v_add_u32_e32 v1, v10, v1
	v_ashrrev_i32_e32 v14, 6, v1
	v_lshlrev_b32_e32 v1, 5, v14
	v_and_b32_e32 v13, 32, v1
	v_bfe_i32 v1, v10, 27, 1
	v_lshrrev_b32_e32 v1, 22, v1
	v_add_u32_e32 v1, v0, v1
	v_and_b32_e32 v1, 0xfffffc00, v1
	v_sub_u32_e32 v0, v0, v1
	v_lshrrev_b32_e32 v1, 4, v0
	v_bitop3_b32 v0, v1, v0, 32 bitop3:0x6c
	v_ashrrev_i32_e32 v1, 31, v0
	s_add_u32 s36, s14, 0x2032000
	v_lshrrev_b32_e32 v1, 26, v1
	s_addc_u32 s37, s15, 0
	s_ashr_i32 s16, s18, 6
	v_add_u32_e32 v1, v0, v1
	s_ashr_i32 s17, s18, 8
	s_lshl_b32 s22, s16, 10
	v_ashrrev_i32_e32 v15, 6, v1
	v_and_b32_e32 v1, 0xc0, v1
	s_lshl_b32 s4, s10, 18
	v_sub_u32_e32 v0, v0, v1
	v_lshlrev_b32_e32 v1, 3, v14
	s_add_u32 s8, s14, s4
	v_ashrrev_i16_sdwa v0, v2, sext(v0) dst_sel:DWORD dst_unused:UNUSED_PAD src0_sel:DWORD src1_sel:BYTE_0
	v_and_b32_e32 v1, -16, v1
	s_addc_u32 s9, s15, 0
	v_bfe_i32 v16, v0, 0, 16
	v_add_u32_e32 v1, v15, v1
	s_add_u32 s4, s8, 0x1300000
	v_add_u32_e32 v0, v13, v16
	v_lshlrev_b32_e32 v2, 10, v1
	s_addc_u32 s5, s9, 0
	s_add_i32 s38, s22, 0
	v_lshl_add_u32 v132, v0, 1, v2
	s_add_i32 m0, s38, 0x10000
	v_mul_lo_u32 v1, v1, s23
	global_load_lds_dwordx4 v132, s[4:5]
	s_add_i32 m0, s38, 0x12000
	s_add_u32 s8, s8, 0x1320000
	global_load_lds_dwordx4 v128, s[4:5]
	s_addc_u32 s9, s9, 0
	s_add_i32 m0, s38, 0x14000
	v_add_lshl_u32 v134, v0, v1, 1
	global_load_lds_dwordx4 v132, s[8:9]
	s_add_i32 m0, s38, 0x16000
	s_add_u32 s24, s36, s33
	s_addc_u32 s25, s37, s11
	s_add_i32 s11, s38, 0x2000
	global_load_lds_dwordx4 v128, s[8:9]
	s_mov_b32 m0, s38
	s_add_u32 s8, s24, 0x1e0000
	global_load_lds_dwordx4 v134, s[24:25]
	s_mov_b32 m0, s11
	s_addc_u32 s9, s25, 0
	s_add_i32 s33, s38, 0x4000
	global_load_lds_dwordx4 v130, s[24:25]
	s_mov_b32 m0, s33
	s_add_i32 s39, s38, 0x6000
	global_load_lds_dwordx4 v134, s[8:9]
	s_mov_b32 m0, s39
	v_mov_b32_e32 v137, 0
	global_load_lds_dwordx4 v130, s[8:9]
	v_mov_b32_e32 v133, v137
	v_mov_b32_e32 v129, v137
	v_mov_b32_e32 v135, v137
	v_mov_b32_e32 v131, v137
	s_cmp_eq_u32 s17, 1
	s_mov_b32 s42, 0
	s_waitcnt vmcnt(0)
	v_lshl_add_u64 v[6:7], s[4:5], 0, v[132:133]
	v_lshl_add_u64 v[4:5], s[4:5], 0, v[128:129]
	v_lshl_add_u64 v[0:1], s[24:25], 0, v[134:135]
	s_cselect_b64 s[8:9], -1, 0
	s_cmp_lg_u32 s17, 1
	v_lshl_add_u64 v[2:3], s[24:25], 0, v[130:131]
	s_cbranch_scc1 .LBB0_852
	s_barrier

.LBB0_861:
	s_lshr_b32 s98, s94, 2
	s_and_b32 s98, s98, 1
	s_add_i32 s98, s98, 64
	s_and_b32 s99, s94, 3
	v_writelane_b32 v214, s98, 0
	v_writelane_b32 v214, s99, 1
	s_movk_i32 s98, 0x22
	v_writelane_b32 v214, s98, 2
	s_and_b32 s98, s94, 7
	s_lshl_b32 s98, s98, 6
	s_add_u32 s98, s98, 0x13fb3800
	s_add_u32 s98, s40, s98
	s_addc_u32 s99, s41, 0
	v_mov_b32_e32 v213, 0
.Lflagw_2:
	global_load_dword v212, v213, s[98:99] sc1
	s_waitcnt vmcnt(0)
	v_readfirstlane_b32 s100, v212
	s_cmp_ge_u32 s100, 2
	s_cbranch_scc1 .Lflagd_2
	s_sleep 2
	s_branch .Lflagw_2
